# k8 + forgetting attention: V in natural key order, P unswapped (8 permlane swaps per tile removed)
# baseline (speedup 1.0000x reference)
.LBB0_558:
	s_lshl_b32 s4, s77, 3
	s_and_b32 s60, s4, 0xffffff00
	s_sub_i32 s4, 0x203f, s60
	s_ashr_i32 s5, s4, 31
	s_lshr_b32 s5, s5, 26
	s_add_i32 s4, s4, s5
	s_ashr_i32 s4, s4, 6
	s_sub_i32 s52, 0x1f40, s60
	s_add_i32 s4, s4, 1
	s_cmpk_lt_i32 s52, 0x1f41
	s_cselect_b32 s78, s4, 0x81
	s_lshl_b32 s4, s77, 8
	s_and_b32 s83, s4, 0x1f00
	s_sub_i32 s4, 0x1f00, s60
	s_add_i32 s86, s83, 0
	s_ashr_i32 s84, s4, 5
	s_and_b32 s4, s77, 31
	s_add_i32 s86, s86, 0x21000
	s_mul_i32 s85, s4, 0x2040
	s_sub_i32 s82, s78, s76
	s_add_i32 s6, s86, s84
	s_lshl_b32 s4, s85, 2
	s_add_u32 s54, s30, s4
	s_addc_u32 s55, s31, 0
	s_ashr_i32 s53, s52, 31
	s_lshl_b64 s[4:5], s[52:53], 2
	s_add_u32 s4, s54, s4
	s_addc_u32 s5, s55, s5
	v_mbcnt_lo_u32_b32 v32, -1, 0
	v_mbcnt_hi_u32_b32 v32, -1, v32
	global_load_dword v0, v193, s[4:5]
	v_add_u32_e32 v204, s64, v32
	v_lshlrev_b32_e32 v1, 3, v32
	v_ashrrev_i32_e32 v195, 4, v204
	v_and_b32_e32 v2, 0x78, v1
	v_and_b32_e32 v3, 0xfffff0, v195
	v_lshlrev_b32_e32 v4, 1, v195
	v_lshrrev_b32_e32 v5, 1, v195
	v_and_b32_e32 v6, 3, v195
	v_add_u32_e32 v215, 32, v195
	v_lshlrev_b32_e32 v192, 1, v2
	v_and_or_b32 v2, v4, 8, v3
	v_and_or_b32 v3, v5, 4, v6
	v_and_b32_e32 v5, 0xfffff0, v215
	v_lshlrev_b32_e32 v6, 1, v215
	v_and_or_b32 v5, v6, 8, v5
	v_bfe_u32 v1, v1, 5, 2
	v_lshrrev_b32_e32 v2, 1, v2
	v_lshrrev_b32_e32 v5, 1, v5
	v_or_b32_e32 v2, v2, v1
	v_or_b32_e32 v1, v5, v1
	v_and_b32_e32 v4, 48, v192
	v_lshlrev_b32_e32 v3, 6, v3
	v_lshlrev_b32_e32 v1, 9, v1
	s_lshl_b32 s5, s77, 1
	v_or3_b32 v1, v1, v3, v4
	s_bfe_u32 s4, s77, 0x10004
	s_and_b32 s5, s5, 30
	v_mov_b32_e32 v1, s6
	s_or_b32 s4, s5, s4
	ds_read_b32 v1, v1
	s_mul_i32 s4, s4, 0x204000
	s_add_u32 s4, s26, s4
	s_addc_u32 s5, s27, 0
	s_add_u32 s6, s4, 0x10200000
	v_lshlrev_b32_e32 v2, 9, v2
	s_addc_u32 s7, s5, 0
	v_or3_b32 v2, v2, v3, v4
	s_add_u32 s8, s4, 0x14280000
	v_lshrrev_b32_e32 v5, 3, v195
	v_bfe_u32 v6, v192, 6, 2
	v_lshl_or_b32 v5, v5, 2, v6
	v_lshlrev_b32_e32 v5, 9, v5
	v_and_b32_e32 v6, 7, v195
	v_lshl_or_b32 v5, v6, 6, v5
	v_and_b32_e32 v6, 48, v192
	v_or_b32_e32 v218, v5, v6
	v_add_u32_e32 v219, 0x2000, v218
	s_addc_u32 s9, s5, 0
	ds_write_b128 v218, v[96:99]
	ds_write_b128 v219, v[100:103]
	s_waitcnt vmcnt(0) lgkmcnt(2)
	v_add_f32_e32 v0, v1, v0
	s_nop 0
	v_readfirstlane_b32 s87, v0
	s_cmp_gt_i32 s82, 1
	s_cselect_b64 s[56:57], -1, 0
	s_lshl_b32 s44, s76, 6
	s_cmp_lt_i32 s82, 2
	v_cmp_gt_i32_e32 vcc, 64, v204
	s_cbranch_scc1 .LBB0_562
	s_add_i32 s58, s44, 64
	v_add_u32_e32 v0, s58, v195
	v_ashrrev_i32_e32 v1, 31, v0
	v_add_u32_e32 v4, s58, v215
	v_lshlrev_b64 v[0:1], 8, v[0:1]
	v_ashrrev_i32_e32 v5, 31, v4
	v_lshl_add_u64 v[2:3], s[8:9], 0, v[0:1]
	v_lshlrev_b64 v[4:5], 8, v[4:5]
	v_lshl_add_u64 v[2:3], v[2:3], 0, v[192:193]
	v_lshl_add_u64 v[6:7], s[8:9], 0, v[4:5]
	v_lshl_add_u64 v[0:1], s[6:7], 0, v[0:1]
	v_lshl_add_u64 v[6:7], v[6:7], 0, v[192:193]
	global_load_dwordx4 v[96:99], v[2:3], off
	global_load_dwordx4 v[100:103], v[6:7], off
	v_lshl_add_u64 v[0:1], v[0:1], 0, v[192:193]
	v_lshl_add_u64 v[2:3], s[6:7], 0, v[4:5]
	v_lshl_add_u64 v[2:3], v[2:3], 0, v[192:193]
	global_load_dwordx4 v[104:107], v[0:1], off
	global_load_dwordx4 v[108:111], v[2:3], off
	s_and_saveexec_b64 s[4:5], vcc
	s_cbranch_execz .LBB0_561
	v_add_u32_e32 v0, s58, v204
	v_ashrrev_i32_e32 v1, 31, v0
	v_lshl_add_u64 v[0:1], v[0:1], 2, s[54:55]
	global_load_dword v203, v[0:1], off

.LBB0_584:
	s_waitcnt vmcnt(3)
	v_add_f32_e32 v96, 0, v173
	v_add_f32_e32 v96, v175, v96
	v_add_f32_e32 v96, v171, v96
	v_add_f32_e32 v96, v174, v96
	v_add_f32_e32 v96, v169, v96
	v_add_f32_e32 v96, v172, v96
	v_add_f32_e32 v96, v168, v96
	v_add_f32_e32 v96, v170, v96
	v_add_f32_e32 v96, v162, v96
	v_add_f32_e32 v96, v165, v96
	v_add_f32_e32 v96, v161, v96
	v_add_f32_e32 v96, v163, v96
	s_waitcnt vmcnt(1)
	v_exp_f32_e32 v104, v126
	v_add_f32_e32 v96, v160, v96
	v_exp_f32_e32 v105, v127
	v_add_f32_e32 v96, v167, v96
	v_exp_f32_e32 v106, v124
	v_add_f32_e32 v96, v164, v96
	v_exp_f32_e32 v107, v125
	v_add_f32_e32 v96, v166, v96
	s_waitcnt vmcnt(0)
	v_exp_f32_e32 v108, v122
	v_add_f32_e32 v96, v104, v96
	v_exp_f32_e32 v109, v123
	v_add_f32_e32 v96, v105, v96
	v_exp_f32_e32 v110, v120
	v_add_f32_e32 v96, v106, v96
	v_exp_f32_e32 v111, v121
	v_add_f32_e32 v96, v107, v96
	v_exp_f32_e32 v118, v118
	v_add_f32_e32 v96, v108, v96
	v_exp_f32_e32 v119, v119
	v_add_f32_e32 v96, v109, v96
	v_exp_f32_e32 v116, v116
	v_add_f32_e32 v96, v110, v96
	v_exp_f32_e32 v117, v117
	v_add_f32_e32 v96, v111, v96
	v_exp_f32_e32 v114, v114
	v_add_f32_e32 v96, v118, v96
	v_exp_f32_e32 v115, v115
	v_add_f32_e32 v96, v119, v96
	v_exp_f32_e32 v112, v112
	v_add_f32_e32 v96, v116, v96
	v_exp_f32_e32 v113, v113
	v_add_f32_e32 v96, v117, v96
	v_add_f32_e32 v96, v114, v96
	v_add_f32_e32 v96, v115, v96
	v_add_f32_e32 v96, v112, v96
	v_add_f32_e32 v229, v113, v96
	v_mov_b32_e32 v230, v229
	v_cvt_pk_bf16_f32 v96, v173, v175
	v_cvt_pk_bf16_f32 v97, v171, v174
	v_cvt_pk_bf16_f32 v98, v169, v172
	v_cvt_pk_bf16_f32 v99, v168, v170
	v_cvt_pk_bf16_f32 v100, v162, v165
	v_cvt_pk_bf16_f32 v101, v161, v163
	v_cvt_pk_bf16_f32 v102, v160, v167
	v_cvt_pk_bf16_f32 v103, v164, v166
	v_cvt_pk_bf16_f32 v104, v104, v105
	v_cvt_pk_bf16_f32 v105, v106, v107
	v_cvt_pk_bf16_f32 v106, v108, v109
	v_cvt_pk_bf16_f32 v107, v110, v111
	v_cvt_pk_bf16_f32 v108, v118, v119
	v_cvt_pk_bf16_f32 v109, v116, v117
	v_cvt_pk_bf16_f32 v110, v114, v115
	v_cvt_pk_bf16_f32 v111, v112, v113
	s_nop 1
	v_permlane32_swap_b32_e32 v229, v230
	v_add_u32_e32 v233, s90, v195
	v_add_u32_e32 v112, 0x80, v233
	v_ashrrev_i32_e32 v113, 31, v112
	v_add_u32_e32 v116, 0xa0, v233
	v_lshlrev_b64 v[112:113], 8, v[112:113]
	v_ashrrev_i32_e32 v117, 31, v116
	v_lshl_add_u64 v[114:115], v[196:197], 0, v[112:113]
	v_lshlrev_b64 v[116:117], 8, v[116:117]
	v_lshl_add_u64 v[112:113], v[198:199], 0, v[112:113]
	v_lshl_add_u64 v[118:119], v[196:197], 0, v[116:117]
	global_load_dwordx4 v[160:163], v[114:115], off
	global_load_dwordx4 v[164:167], v[118:119], off
	v_lshl_add_u64 v[114:115], v[198:199], 0, v[116:117]
	global_load_dwordx4 v[168:171], v[112:113], off
	global_load_dwordx4 v[172:175], v[114:115], off
	s_and_saveexec_b64 s[58:59], s[6:7]
	s_cbranch_execz .LBB0_586
	v_add_u32_e32 v112, s90, v204
	v_add_u32_e32 v112, 0x80, v112
	v_ashrrev_i32_e32 v113, 31, v112
	v_lshl_add_u64 v[112:113], v[112:113], 2, s[54:55]
	global_load_dword v203, v[112:113], off

.LBB0_602:
	v_exp_f32_e32 v81, v83
	v_exp_f32_e32 v83, v87
	v_exp_f32_e32 v87, v91
	v_exp_f32_e32 v91, v95
	v_exp_f32_e32 v95, v176
	v_add_f32_e32 v176, 0, v64
	v_add_f32_e32 v176, v65, v176
	v_add_f32_e32 v176, v66, v176
	v_add_f32_e32 v176, v67, v176
	v_add_f32_e32 v176, v68, v176
	v_add_f32_e32 v176, v69, v176
	v_add_f32_e32 v176, v70, v176
	v_add_f32_e32 v176, v71, v176
	v_add_f32_e32 v176, v72, v176
	v_add_f32_e32 v176, v73, v176
	v_add_f32_e32 v176, v74, v176
	v_add_f32_e32 v176, v75, v176
	v_exp_f32_e32 v80, v82
	v_add_f32_e32 v176, v76, v176
	v_add_f32_e32 v176, v77, v176
	v_exp_f32_e32 v82, v86
	v_add_f32_e32 v176, v78, v176
	v_add_f32_e32 v176, v79, v176
	v_exp_f32_e32 v84, v88
	v_add_f32_e32 v176, v80, v176
	v_exp_f32_e32 v85, v89
	v_add_f32_e32 v176, v81, v176
	v_exp_f32_e32 v86, v90
	v_add_f32_e32 v176, v82, v176
	v_add_f32_e32 v176, v83, v176
	v_exp_f32_e32 v88, v92
	v_add_f32_e32 v176, v84, v176
	v_exp_f32_e32 v89, v93
	v_add_f32_e32 v176, v85, v176
	v_exp_f32_e32 v90, v94
	v_add_f32_e32 v176, v86, v176
	v_add_f32_e32 v176, v87, v176
	v_exp_f32_e32 v92, v177
	v_add_f32_e32 v176, v88, v176
	v_exp_f32_e32 v93, v178
	v_add_f32_e32 v176, v89, v176
	v_exp_f32_e32 v94, v179
	v_add_f32_e32 v176, v90, v176
	v_add_f32_e32 v176, v91, v176
	v_add_f32_e32 v176, v92, v176
	v_add_f32_e32 v176, v93, v176
	v_add_f32_e32 v176, v94, v176
	v_add_f32_e32 v234, v95, v176
	v_mov_b32_e32 v235, v234
	v_cvt_pk_bf16_f32 v176, v64, v65
	v_cvt_pk_bf16_f32 v177, v66, v67
	v_cvt_pk_bf16_f32 v178, v68, v69
	v_cvt_pk_bf16_f32 v179, v70, v71
	v_cvt_pk_bf16_f32 v180, v72, v73
	v_cvt_pk_bf16_f32 v181, v74, v75
	v_cvt_pk_bf16_f32 v182, v76, v77
	v_cvt_pk_bf16_f32 v183, v78, v79
	v_cvt_pk_bf16_f32 v184, v80, v81
	v_cvt_pk_bf16_f32 v185, v82, v83
	v_cvt_pk_bf16_f32 v186, v84, v85
	v_cvt_pk_bf16_f32 v187, v86, v87
	v_cvt_pk_bf16_f32 v188, v88, v89
	v_cvt_pk_bf16_f32 v189, v90, v91
	v_cvt_pk_bf16_f32 v190, v92, v93
	v_cvt_pk_bf16_f32 v191, v94, v95
	s_nop 1
	v_permlane32_swap_b32_e32 v234, v235
	s_add_i32 s14, s89, -3
	s_cmp_lt_i32 s14, s82
	s_cselect_b64 s[58:59], -1, 0
	s_cmp_ge_i32 s14, s82
	s_cbranch_scc1 .LBB0_606
	v_add_u32_e32 v160, 0xc0, v233
	v_add_u32_e32 v162, 0xe0, v233
	v_ashrrev_i32_e32 v161, 31, v160
	v_ashrrev_i32_e32 v163, 31, v162
	v_lshlrev_b64 v[168:169], 8, v[160:161]
	v_lshlrev_b64 v[170:171], 8, v[162:163]
	v_lshl_add_u64 v[160:161], v[196:197], 0, v[168:169]
	v_lshl_add_u64 v[164:165], v[196:197], 0, v[170:171]
	v_lshl_add_u64 v[168:169], v[198:199], 0, v[168:169]
	v_lshl_add_u64 v[172:173], v[198:199], 0, v[170:171]
	global_load_dwordx4 v[160:163], v[160:161], off
	s_nop 0
	global_load_dwordx4 v[164:167], v[164:165], off
	s_nop 0
	global_load_dwordx4 v[168:171], v[168:169], off
	s_nop 0
	global_load_dwordx4 v[172:175], v[172:173], off
	s_and_saveexec_b64 s[62:63], s[6:7]
	s_cbranch_execz .LBB0_605
	v_add_u32_e32 v203, s90, v204
	v_add_u32_e32 v206, 0xc0, v203
	v_ashrrev_i32_e32 v207, 31, v206
	v_lshl_add_u64 v[206:207], v[206:207], 2, s[54:55]
	global_load_dword v203, v[206:207], off

.LBB0_649:
	s_or_b64 exec, exec, s[52:53]
	s_lshl_b32 s8, s57, 10
	s_and_b32 s8, s8, 0xffff8000
	s_sub_i32 s8, s58, s8
	s_add_i32 s44, s8, 0x61ba000
	s_lshl_b64 s[8:9], s[44:45], 1
	v_or_b32_e32 v192, s40, v205
	s_add_u32 s8, s26, s8
	v_lshlrev_b64 v[128:129], 8, v[192:193]
	s_addc_u32 s9, s27, s9
	v_lshl_add_u64 v[128:129], s[8:9], 0, v[128:129]
	v_mov_b32_e32 v195, v193
	v_lshl_add_u64 v[128:129], v[128:129], 0, v[194:195]
	global_load_dwordx4 v[156:159], v[128:129], off
	global_load_dwordx4 v[152:155], v[128:129], off offset:32
	global_load_dwordx4 v[148:151], v[128:129], off offset:64
	global_load_dwordx4 v[132:135], v[128:129], off offset:96
	global_load_dwordx4 v[136:139], v[128:129], off offset:128
	global_load_dwordx4 v[140:143], v[128:129], off offset:160
	global_load_dwordx4 v[144:147], v[128:129], off offset:192
	s_nop 0
	global_load_dwordx4 v[128:131], v[128:129], off offset:224
	v_exp_f32_e32 v187, v112
	v_add_f32_e32 v112, 0, v173
	v_add_f32_e32 v112, v175, v112
	v_add_f32_e32 v112, v171, v112
	v_add_f32_e32 v112, v174, v112
	v_add_f32_e32 v112, v169, v112
	v_add_f32_e32 v112, v172, v112
	v_add_f32_e32 v112, v168, v112
	v_add_f32_e32 v112, v170, v112
	v_add_f32_e32 v112, v162, v112
	v_add_f32_e32 v112, v165, v112
	v_add_f32_e32 v112, v161, v112
	v_add_f32_e32 v112, v163, v112
	v_exp_f32_e32 v126, v126
	v_add_f32_e32 v112, v160, v112
	v_exp_f32_e32 v127, v127
	v_add_f32_e32 v112, v167, v112
	v_exp_f32_e32 v124, v124
	v_add_f32_e32 v112, v164, v112
	v_exp_f32_e32 v125, v125
	v_add_f32_e32 v112, v166, v112
	v_exp_f32_e32 v122, v122
	v_add_f32_e32 v112, v126, v112
	v_exp_f32_e32 v123, v123
	v_add_f32_e32 v112, v127, v112
	v_exp_f32_e32 v179, v120
	v_add_f32_e32 v112, v124, v112
	v_exp_f32_e32 v180, v121
	v_add_f32_e32 v112, v125, v112
	v_exp_f32_e32 v181, v118
	v_add_f32_e32 v112, v122, v112
	v_exp_f32_e32 v182, v119
	v_add_f32_e32 v112, v123, v112
	v_exp_f32_e32 v183, v116
	v_add_f32_e32 v112, v179, v112
	v_exp_f32_e32 v184, v117
	v_add_f32_e32 v112, v180, v112
	v_exp_f32_e32 v185, v114
	v_add_f32_e32 v112, v181, v112
	v_exp_f32_e32 v186, v115
	v_add_f32_e32 v112, v182, v112
	v_add_f32_e32 v112, v183, v112
	v_exp_f32_e32 v188, v113
	v_add_f32_e32 v112, v184, v112
	v_add_f32_e32 v112, v185, v112
	v_add_f32_e32 v112, v186, v112
	v_add_f32_e32 v112, v187, v112
	v_add_f32_e32 v176, v188, v112
	v_mov_b32_e32 v177, v176
	v_cvt_pk_bf16_f32 v112, v173, v175
	v_cvt_pk_bf16_f32 v113, v171, v174
	v_cvt_pk_bf16_f32 v114, v169, v172
	v_cvt_pk_bf16_f32 v115, v168, v170
	v_cvt_pk_bf16_f32 v116, v162, v165
	v_cvt_pk_bf16_f32 v117, v161, v163
	v_cvt_pk_bf16_f32 v118, v160, v167
	v_cvt_pk_bf16_f32 v119, v164, v166
	v_cvt_pk_bf16_f32 v120, v126, v127
	v_cvt_pk_bf16_f32 v121, v124, v125
	v_cvt_pk_bf16_f32 v122, v122, v123
	v_cvt_pk_bf16_f32 v123, v179, v180
	v_cvt_pk_bf16_f32 v124, v181, v182
	v_cvt_pk_bf16_f32 v125, v183, v184
	v_cvt_pk_bf16_f32 v126, v185, v186
	v_cvt_pk_bf16_f32 v127, v187, v188
	s_nop 1
	v_permlane32_swap_b32_e32 v176, v177
	s_or_b32 s8, s82, 0x3fffffe
	s_add_i32 s8, s8, s78
	s_lshl_b32 s14, s8, 6
	s_cmp_le_i32 s14, s80
	s_cselect_b64 s[8:9], -1, 0
	s_or_b32 s14, s14, 63
	s_cmp_ge_i32 s14, s81
	s_cselect_b64 s[14:15], -1, 0
	s_and_b64 s[8:9], s[8:9], s[14:15]
	s_andn2_b64 vcc, exec, s[8:9]
	s_cbranch_vccnz .LBB0_651
	ds_read_b64_tr_b16 v[160:161], v213 offset:0
	ds_read_b64_tr_b16 v[162:163], v213 offset:0x800
	ds_read_b64_tr_b16 v[164:165], v213 offset:0x1000
	ds_read_b64_tr_b16 v[166:167], v213 offset:0x1800
	ds_read_b64_tr_b16 v[168:169], v213 offset:0x2000
	ds_read_b64_tr_b16 v[170:171], v213 offset:0x2800
	ds_read_b64_tr_b16 v[172:173], v213 offset:0x3000
	ds_read_b64_tr_b16 v[174:175], v213 offset:0x3800
	s_waitcnt lgkmcnt(0)
	s_nop 0
	v_mfma_f32_32x32x16_bf16 v[32:47], v[112:115], v[160:163], v[32:47]
	ds_read_b64_tr_b16 v[160:161], v213 offset:0x200
	ds_read_b64_tr_b16 v[162:163], v213 offset:0xa00
	v_mfma_f32_32x32x16_bf16 v[32:47], v[116:119], v[164:167], v[32:47]
	ds_read_b64_tr_b16 v[164:165], v213 offset:0x1200
	ds_read_b64_tr_b16 v[166:167], v213 offset:0x1a00
	v_mfma_f32_32x32x16_bf16 v[32:47], v[120:123], v[168:171], v[32:47]
	ds_read_b64_tr_b16 v[168:169], v213 offset:0x2200
	ds_read_b64_tr_b16 v[170:171], v213 offset:0x2a00
	ds_read_b64_tr_b16 v[180:181], v213 offset:0x3200
	ds_read_b64_tr_b16 v[182:183], v213 offset:0x3a00
	s_waitcnt lgkmcnt(0)
	v_mfma_f32_32x32x16_bf16 v[32:47], v[124:127], v[172:175], v[32:47]
	v_mfma_f32_32x32x16_bf16 v[48:63], v[112:115], v[160:163], v[48:63]
	ds_read_b64_tr_b16 v[160:161], v213 offset:0x400
	ds_read_b64_tr_b16 v[162:163], v213 offset:0xc00
	v_mfma_f32_32x32x16_bf16 v[48:63], v[116:119], v[164:167], v[48:63]
	ds_read_b64_tr_b16 v[164:165], v213 offset:0x1400
	ds_read_b64_tr_b16 v[166:167], v213 offset:0x1c00
	v_mfma_f32_32x32x16_bf16 v[48:63], v[120:123], v[168:171], v[48:63]
	ds_read_b64_tr_b16 v[168:169], v213 offset:0x2400
	ds_read_b64_tr_b16 v[170:171], v213 offset:0x2c00
	ds_read_b64_tr_b16 v[172:173], v213 offset:0x3400
	ds_read_b64_tr_b16 v[174:175], v213 offset:0x3c00
	s_waitcnt lgkmcnt(0)
	v_mfma_f32_32x32x16_bf16 v[48:63], v[124:127], v[180:183], v[48:63]
	v_mfma_f32_32x32x16_bf16 v[16:31], v[112:115], v[160:163], v[16:31]
	ds_read_b64_tr_b16 v[160:161], v213 offset:0x600
	ds_read_b64_tr_b16 v[162:163], v213 offset:0xe00
	v_mfma_f32_32x32x16_bf16 v[16:31], v[116:119], v[164:167], v[16:31]
	ds_read_b64_tr_b16 v[164:165], v213 offset:0x1600
	ds_read_b64_tr_b16 v[166:167], v213 offset:0x1e00
	v_mfma_f32_32x32x16_bf16 v[16:31], v[120:123], v[168:171], v[16:31]
	ds_read_b64_tr_b16 v[168:169], v213 offset:0x2600
	ds_read_b64_tr_b16 v[170:171], v213 offset:0x2e00
	ds_read_b64_tr_b16 v[180:181], v213 offset:0x3600
	ds_read_b64_tr_b16 v[182:183], v213 offset:0x3e00
	s_waitcnt lgkmcnt(0)
	v_mfma_f32_32x32x16_bf16 v[16:31], v[124:127], v[172:175], v[16:31]
	v_mfma_f32_32x32x16_bf16 v[0:15], v[112:115], v[160:163], v[0:15]
	v_mfma_f32_32x32x16_bf16 v[0:15], v[116:119], v[164:167], v[0:15]
	v_mfma_f32_32x32x16_bf16 v[0:15], v[120:123], v[168:171], v[0:15]
	v_mfma_f32_32x32x16_bf16 v[0:15], v[124:127], v[180:183], v[0:15]

.LBB0_659:
	v_cndmask_b32_e64 v93, v93, v178, s[8:9]
	v_mul_f32_e32 v93, 0xbe0293ee, v93
	v_fmamk_f32 v114, v114, 0x3e0293ee, v93
	v_fmamk_f32 v115, v115, 0x3e0293ee, v93
	v_fmamk_f32 v94, v82, 0x3e0293ee, v93
	v_exp_f32_e32 v82, v114
	v_fmamk_f32 v117, v112, 0x3e0293ee, v93
	v_fmamk_f32 v112, v84, 0x3e0293ee, v93
	v_exp_f32_e32 v84, v115
	v_fmamk_f32 v118, v113, 0x3e0293ee, v93
	v_fmamk_f32 v121, v78, 0x3e0293ee, v93
	v_exp_f32_e32 v78, v117
	v_fmamk_f32 v76, v76, 0x3e0293ee, v93
	v_fmamk_f32 v95, v83, 0x3e0293ee, v93
	v_exp_f32_e32 v83, v118
	v_fmamk_f32 v64, v64, 0x3e0293ee, v93
	v_fmamk_f32 v77, v77, 0x3e0293ee, v93
	v_fmamk_f32 v119, v66, 0x3e0293ee, v93
	v_exp_f32_e32 v66, v76
	v_exp_f32_e32 v118, v64
	v_add_f32_e32 v64, 0, v82
	v_fmamk_f32 v70, v70, 0x3e0293ee, v93
	v_fmamk_f32 v122, v79, 0x3e0293ee, v93
	v_exp_f32_e32 v79, v77
	v_add_f32_e32 v64, v84, v64
	v_fmamk_f32 v71, v71, 0x3e0293ee, v93
	v_fmamk_f32 v120, v67, 0x3e0293ee, v93
	v_exp_f32_e32 v67, v70
	v_add_f32_e32 v64, v78, v64
	v_fmamk_f32 v72, v72, 0x3e0293ee, v93
	v_exp_f32_e32 v77, v71
	v_add_f32_e32 v64, v83, v64
	v_fmamk_f32 v73, v73, 0x3e0293ee, v93
	v_fmamk_f32 v113, v68, 0x3e0293ee, v93
	v_exp_f32_e32 v68, v72
	v_add_f32_e32 v64, v66, v64
	v_fmamk_f32 v74, v74, 0x3e0293ee, v93
	v_exp_f32_e32 v76, v73
	v_add_f32_e32 v64, v79, v64
	v_fmamk_f32 v75, v75, 0x3e0293ee, v93
	v_exp_f32_e32 v73, v74
	v_add_f32_e32 v64, v67, v64
	v_exp_f32_e32 v75, v75
	v_add_f32_e32 v64, v77, v64
	v_exp_f32_e32 v70, v119
	v_add_f32_e32 v64, v68, v64
	v_exp_f32_e32 v74, v120
	v_add_f32_e32 v64, v76, v64
	v_exp_f32_e32 v71, v121
	v_add_f32_e32 v64, v73, v64
	v_fmamk_f32 v80, v80, 0x3e0293ee, v93
	v_exp_f32_e32 v72, v122
	v_add_f32_e32 v64, v75, v64
	v_fmamk_f32 v81, v81, 0x3e0293ee, v93
	v_exp_f32_e32 v114, v80
	v_add_f32_e32 v64, v70, v64
	v_exp_f32_e32 v115, v81
	v_add_f32_e32 v64, v74, v64
	v_exp_f32_e32 v94, v94
	v_add_f32_e32 v64, v71, v64
	v_exp_f32_e32 v95, v95
	v_add_f32_e32 v64, v72, v64
	v_fmamk_f32 v85, v85, 0x3e0293ee, v93
	v_exp_f32_e32 v112, v112
	v_add_f32_e32 v64, v114, v64
	v_fmamk_f32 v86, v86, 0x3e0293ee, v93
	v_exp_f32_e32 v85, v85
	v_add_f32_e32 v64, v115, v64
	v_fmamk_f32 v87, v87, 0x3e0293ee, v93
	v_exp_f32_e32 v86, v86
	v_add_f32_e32 v64, v94, v64
	v_fmamk_f32 v88, v88, 0x3e0293ee, v93
	v_exp_f32_e32 v87, v87
	v_add_f32_e32 v64, v95, v64
	v_fmamk_f32 v89, v89, 0x3e0293ee, v93
	v_exp_f32_e32 v88, v88
	v_add_f32_e32 v64, v112, v64
	v_fmamk_f32 v90, v90, 0x3e0293ee, v93
	v_exp_f32_e32 v89, v89
	v_add_f32_e32 v64, v85, v64
	v_fmamk_f32 v91, v91, 0x3e0293ee, v93
	v_exp_f32_e32 v90, v90
	v_add_f32_e32 v64, v86, v64
	v_exp_f32_e32 v91, v91
	v_add_f32_e32 v64, v87, v64
	v_fmamk_f32 v69, v69, 0x3e0293ee, v93
	v_exp_f32_e32 v113, v113
	v_add_f32_e32 v64, v88, v64
	v_exp_f32_e32 v117, v69
	v_add_f32_e32 v64, v89, v64
	v_fmac_f32_e32 v93, 0x3e0293ee, v65
	v_add_f32_e32 v64, v90, v64
	v_exp_f32_e32 v93, v93
	v_add_f32_e32 v64, v91, v64
	v_add_f32_e32 v64, v113, v64
	v_add_f32_e32 v64, v117, v64
	v_add_f32_e32 v64, v118, v64
	v_add_f32_e32 v80, v93, v64
	v_mov_b32_e32 v81, v80
	v_cvt_pk_bf16_f32 v64, v82, v84
	v_cvt_pk_bf16_f32 v65, v78, v83
	v_cvt_pk_bf16_f32 v66, v66, v79
	v_cvt_pk_bf16_f32 v67, v67, v77
	v_cvt_pk_bf16_f32 v68, v68, v76
	v_cvt_pk_bf16_f32 v69, v73, v75
	v_cvt_pk_bf16_f32 v70, v70, v74
	v_cvt_pk_bf16_f32 v71, v71, v72
	v_cvt_pk_bf16_f32 v72, v114, v115
	v_cvt_pk_bf16_f32 v73, v94, v95
	v_cvt_pk_bf16_f32 v74, v112, v85
	v_cvt_pk_bf16_f32 v75, v86, v87
	v_cvt_pk_bf16_f32 v76, v88, v89
	v_cvt_pk_bf16_f32 v77, v90, v91
	v_cvt_pk_bf16_f32 v78, v113, v117
	v_cvt_pk_bf16_f32 v79, v118, v93
	s_nop 1
	v_permlane32_swap_b32_e32 v80, v81
	s_and_b64 vcc, exec, s[6:7]
	s_cbranch_vccnz .LBB0_661
	ds_read_b64_tr_b16 v[82:83], v213 offset:0x4000
	ds_read_b64_tr_b16 v[84:85], v213 offset:0x4800
	ds_read_b64_tr_b16 v[86:87], v213 offset:0x5000
	ds_read_b64_tr_b16 v[88:89], v213 offset:0x5800
	ds_read_b64_tr_b16 v[112:113], v213 offset:0x6000
	ds_read_b64_tr_b16 v[114:115], v213 offset:0x6800
	ds_read_b64_tr_b16 v[118:119], v213 offset:0x7000
	ds_read_b64_tr_b16 v[120:121], v213 offset:0x7800
	s_waitcnt lgkmcnt(0)
	s_nop 0
	v_mfma_f32_32x32x16_bf16 v[32:47], v[64:67], v[82:85], v[32:47]
	ds_read_b64_tr_b16 v[82:83], v213 offset:0x4200
	ds_read_b64_tr_b16 v[84:85], v213 offset:0x4a00
	v_mfma_f32_32x32x16_bf16 v[32:47], v[68:71], v[86:89], v[32:47]
	ds_read_b64_tr_b16 v[86:87], v213 offset:0x5200
	ds_read_b64_tr_b16 v[88:89], v213 offset:0x5a00
	v_mfma_f32_32x32x16_bf16 v[32:47], v[72:75], v[112:115], v[32:47]
	ds_read_b64_tr_b16 v[112:113], v213 offset:0x6200
	ds_read_b64_tr_b16 v[114:115], v213 offset:0x6a00
	ds_read_b64_tr_b16 v[122:123], v213 offset:0x7200
	ds_read_b64_tr_b16 v[124:125], v213 offset:0x7a00
	s_waitcnt lgkmcnt(0)
	v_mfma_f32_32x32x16_bf16 v[32:47], v[76:79], v[118:121], v[32:47]
	v_mfma_f32_32x32x16_bf16 v[48:63], v[64:67], v[82:85], v[48:63]
	ds_read_b64_tr_b16 v[82:83], v213 offset:0x4400
	ds_read_b64_tr_b16 v[84:85], v213 offset:0x4c00
	v_mfma_f32_32x32x16_bf16 v[48:63], v[68:71], v[86:89], v[48:63]
	ds_read_b64_tr_b16 v[86:87], v213 offset:0x5400
	ds_read_b64_tr_b16 v[88:89], v213 offset:0x5c00
	v_mfma_f32_32x32x16_bf16 v[48:63], v[72:75], v[112:115], v[48:63]
	ds_read_b64_tr_b16 v[112:113], v213 offset:0x6400
	ds_read_b64_tr_b16 v[114:115], v213 offset:0x6c00
	ds_read_b64_tr_b16 v[118:119], v213 offset:0x7400
	ds_read_b64_tr_b16 v[120:121], v213 offset:0x7c00
	s_waitcnt lgkmcnt(0)
	v_mfma_f32_32x32x16_bf16 v[48:63], v[76:79], v[122:125], v[48:63]
	v_mfma_f32_32x32x16_bf16 v[16:31], v[64:67], v[82:85], v[16:31]
	ds_read_b64_tr_b16 v[82:83], v213 offset:0x4600
	ds_read_b64_tr_b16 v[84:85], v213 offset:0x4e00
	v_mfma_f32_32x32x16_bf16 v[16:31], v[68:71], v[86:89], v[16:31]
	ds_read_b64_tr_b16 v[86:87], v213 offset:0x5600
	ds_read_b64_tr_b16 v[88:89], v213 offset:0x5e00
	v_mfma_f32_32x32x16_bf16 v[16:31], v[72:75], v[112:115], v[16:31]
	ds_read_b64_tr_b16 v[112:113], v213 offset:0x6600
	ds_read_b64_tr_b16 v[114:115], v213 offset:0x6e00
	ds_read_b64_tr_b16 v[122:123], v213 offset:0x7600
	ds_read_b64_tr_b16 v[124:125], v213 offset:0x7e00
	s_waitcnt lgkmcnt(0)
	v_mfma_f32_32x32x16_bf16 v[16:31], v[76:79], v[118:121], v[16:31]
	v_mfma_f32_32x32x16_bf16 v[0:15], v[64:67], v[82:85], v[0:15]
	v_mfma_f32_32x32x16_bf16 v[0:15], v[68:71], v[86:89], v[0:15]
	v_mfma_f32_32x32x16_bf16 v[0:15], v[72:75], v[112:115], v[0:15]
	v_mfma_f32_32x32x16_bf16 v[0:15], v[76:79], v[122:125], v[0:15]
